# prologue cache f32->bf16 conversion loops rewritten: 4x unrolled, two register sets, next batch loads issued before convert/store (was 2 loads in flight with vmcnt(0) per iteration)
# speedup vs baseline: 1.0018x; 1.0018x over previous
; __device__ __forceinline__ unsigned pk2(float lo, float hi) { f32x2 v = {lo, hi}; bf16x2_hw b = __builtin_convertvector(v, bf16x2_hw); return __builtin_bit_cast(unsigned, b); }
; __device__ __forceinline__ void cvt8(const float* src, bf16* dst, size_t n8, size_t gt, size_t ngt) {
;     for (size_t i = gt; i < n8; i += ngt) { const f32x4 a = __builtin_nontemporal_load((const f32x4*)src + 2 * i), b = __builtin_nontemporal_load((const f32x4*)src + 2 * i + 1);
;         ((u32x4*)dst)[i] = (u32x4){pk2(a[0], a[1]), pk2(a[2], a[3]), pk2(b[0], b[1]), pk2(b[2], b[3])}; }
; }
; __device__ __forceinline__ void phase_prologue(const Args& a, LAS unsigned char* lds, int gw, int ngw, int lane, int wave) {
;     ...
;     unsigned char* cb = ws + WS_CACHE;
;     cvt8(a.in[2], (bf16*)(cb + C_KDC), (size_t)CACHE_ROWS * 128, gt, ngt);
;     cvt8(a.in[3], (bf16*)(cb + C_VDC), (size_t)CACHE_ROWS * 128, gt, ngt);
.LBB0_83:
	v_lshlrev_b32_e32 v2, 5, v66
	v_mov_b32_e32 v3, 0
	v_lshlrev_b32_e32 v4, 4, v66
	v_mov_b32_e32 v5, 0
	s_lshl_b64 s[14:15], s[6:7], 11
	s_add_u32 s16, s10, s14
	s_addc_u32 s17, s11, s15
	v_lshl_add_u64 v[14:15], s[16:17], 0, v[2:3]
	s_add_u32 s16, s12, s14
	s_addc_u32 s17, s13, s15
	v_lshl_add_u64 v[10:11], s[16:17], 0, v[2:3]
	s_add_u32 s16, s49, s14
	s_addc_u32 s17, s48, s15
	v_lshl_add_u64 v[16:17], s[16:17], 0, v[2:3]
	s_add_u32 s16, s47, s14
	s_addc_u32 s17, s46, s15
	v_lshl_add_u64 v[18:19], s[16:17], 0, v[2:3]
	s_lshl_b64 s[16:17], s[90:91], 5
	s_lshl_b64 s[18:19], s[90:91], 4
	s_lshl_b32 s10, s90, 2
	s_mul_i32 s11, s90, 3
	s_lshl_b64 s[12:13], s[6:7], 10
	s_add_u32 s12, s4, s12
	s_addc_u32 s13, s5, s13
	s_add_u32 s12, s12, 0x2de00000
	s_addc_u32 s13, s13, 0
	v_lshl_add_u64 v[12:13], s[12:13], 0, v[4:5]
	s_mov_b32 s14, s2
	s_sub_i32 s15, 0x400000, s11
	s_cmp_lt_i32 s14, s15
	s_cbranch_scc0 .Lcvk_rem
	global_load_dwordx4 v[100:103], v[10:11], off nt
	global_load_dwordx4 v[104:107], v[10:11], off offset:16 nt
	v_lshl_add_u64 v[10:11], v[10:11], 0, s[16:17]
	global_load_dwordx4 v[108:111], v[10:11], off nt
	global_load_dwordx4 v[112:115], v[10:11], off offset:16 nt
	v_lshl_add_u64 v[10:11], v[10:11], 0, s[16:17]
	global_load_dwordx4 v[116:119], v[10:11], off nt
	global_load_dwordx4 v[120:123], v[10:11], off offset:16 nt
	v_lshl_add_u64 v[10:11], v[10:11], 0, s[16:17]
	global_load_dwordx4 v[124:127], v[10:11], off nt
	global_load_dwordx4 v[128:131], v[10:11], off offset:16 nt
	v_lshl_add_u64 v[10:11], v[10:11], 0, s[16:17]
	s_add_u32 s14, s14, s10
.Lcvk_loop:
	s_cmp_lt_i32 s14, s15
	s_cbranch_scc0 .Lcvk_tail_a
	global_load_dwordx4 v[132:135], v[10:11], off nt
	global_load_dwordx4 v[136:139], v[10:11], off offset:16 nt
	v_lshl_add_u64 v[10:11], v[10:11], 0, s[16:17]
	global_load_dwordx4 v[140:143], v[10:11], off nt
	global_load_dwordx4 v[144:147], v[10:11], off offset:16 nt
	v_lshl_add_u64 v[10:11], v[10:11], 0, s[16:17]
	global_load_dwordx4 v[148:151], v[10:11], off nt
	global_load_dwordx4 v[152:155], v[10:11], off offset:16 nt
	v_lshl_add_u64 v[10:11], v[10:11], 0, s[16:17]
	global_load_dwordx4 v[156:159], v[10:11], off nt
	global_load_dwordx4 v[160:163], v[10:11], off offset:16 nt
	v_lshl_add_u64 v[10:11], v[10:11], 0, s[16:17]
	s_add_u32 s14, s14, s10
	s_waitcnt vmcnt(14)
	v_cvt_pk_bf16_f32 v100, v100, v101
	v_cvt_pk_bf16_f32 v101, v102, v103
	v_cvt_pk_bf16_f32 v102, v104, v105
	v_cvt_pk_bf16_f32 v103, v106, v107
	global_store_dwordx4 v[12:13], v[100:103], off
	v_lshl_add_u64 v[12:13], v[12:13], 0, s[18:19]
	s_waitcnt vmcnt(13)
	v_cvt_pk_bf16_f32 v108, v108, v109
	v_cvt_pk_bf16_f32 v109, v110, v111
	v_cvt_pk_bf16_f32 v110, v112, v113
	v_cvt_pk_bf16_f32 v111, v114, v115
	global_store_dwordx4 v[12:13], v[108:111], off
	v_lshl_add_u64 v[12:13], v[12:13], 0, s[18:19]
	s_waitcnt vmcnt(12)
	v_cvt_pk_bf16_f32 v116, v116, v117
	v_cvt_pk_bf16_f32 v117, v118, v119
	v_cvt_pk_bf16_f32 v118, v120, v121
	v_cvt_pk_bf16_f32 v119, v122, v123
	global_store_dwordx4 v[12:13], v[116:119], off
	v_lshl_add_u64 v[12:13], v[12:13], 0, s[18:19]
	s_waitcnt vmcnt(11)
	v_cvt_pk_bf16_f32 v124, v124, v125
	v_cvt_pk_bf16_f32 v125, v126, v127
	v_cvt_pk_bf16_f32 v126, v128, v129
	v_cvt_pk_bf16_f32 v127, v130, v131
	global_store_dwordx4 v[12:13], v[124:127], off
	v_lshl_add_u64 v[12:13], v[12:13], 0, s[18:19]
	s_cmp_lt_i32 s14, s15
	s_cbranch_scc0 .Lcvk_tail_b
	global_load_dwordx4 v[100:103], v[10:11], off nt
	global_load_dwordx4 v[104:107], v[10:11], off offset:16 nt
	v_lshl_add_u64 v[10:11], v[10:11], 0, s[16:17]
	global_load_dwordx4 v[108:111], v[10:11], off nt
	global_load_dwordx4 v[112:115], v[10:11], off offset:16 nt
	v_lshl_add_u64 v[10:11], v[10:11], 0, s[16:17]
	global_load_dwordx4 v[116:119], v[10:11], off nt
	global_load_dwordx4 v[120:123], v[10:11], off offset:16 nt
	v_lshl_add_u64 v[10:11], v[10:11], 0, s[16:17]
	global_load_dwordx4 v[124:127], v[10:11], off nt
	global_load_dwordx4 v[128:131], v[10:11], off offset:16 nt
	v_lshl_add_u64 v[10:11], v[10:11], 0, s[16:17]
	s_add_u32 s14, s14, s10
	s_waitcnt vmcnt(14)
	v_cvt_pk_bf16_f32 v132, v132, v133
	v_cvt_pk_bf16_f32 v133, v134, v135
	v_cvt_pk_bf16_f32 v134, v136, v137
	v_cvt_pk_bf16_f32 v135, v138, v139
	global_store_dwordx4 v[12:13], v[132:135], off
	v_lshl_add_u64 v[12:13], v[12:13], 0, s[18:19]
	s_waitcnt vmcnt(13)
	v_cvt_pk_bf16_f32 v140, v140, v141
	v_cvt_pk_bf16_f32 v141, v142, v143
	v_cvt_pk_bf16_f32 v142, v144, v145
	v_cvt_pk_bf16_f32 v143, v146, v147
	global_store_dwordx4 v[12:13], v[140:143], off
	v_lshl_add_u64 v[12:13], v[12:13], 0, s[18:19]
	s_waitcnt vmcnt(12)
	v_cvt_pk_bf16_f32 v148, v148, v149
	v_cvt_pk_bf16_f32 v149, v150, v151
	v_cvt_pk_bf16_f32 v150, v152, v153
	v_cvt_pk_bf16_f32 v151, v154, v155
	global_store_dwordx4 v[12:13], v[148:151], off
	v_lshl_add_u64 v[12:13], v[12:13], 0, s[18:19]
	s_waitcnt vmcnt(11)
	v_cvt_pk_bf16_f32 v156, v156, v157
	v_cvt_pk_bf16_f32 v157, v158, v159
	v_cvt_pk_bf16_f32 v158, v160, v161
	v_cvt_pk_bf16_f32 v159, v162, v163
	global_store_dwordx4 v[12:13], v[156:159], off
	v_lshl_add_u64 v[12:13], v[12:13], 0, s[18:19]
	s_branch .Lcvk_loop
; __device__ __forceinline__ unsigned pk2(float lo, float hi) { f32x2 v = {lo, hi}; bf16x2_hw b = __builtin_convertvector(v, bf16x2_hw); return __builtin_bit_cast(unsigned, b); }
; __device__ __forceinline__ void cvt8(const float* src, bf16* dst, size_t n8, size_t gt, size_t ngt) {
;     for (size_t i = gt; i < n8; i += ngt) { const f32x4 a = __builtin_nontemporal_load((const f32x4*)src + 2 * i), b = __builtin_nontemporal_load((const f32x4*)src + 2 * i + 1);
;         ((u32x4*)dst)[i] = (u32x4){pk2(a[0], a[1]), pk2(a[2], a[3]), pk2(b[0], b[1]), pk2(b[2], b[3])}; }
; }
; __device__ __forceinline__ void phase_prologue(const Args& a, LAS unsigned char* lds, int gw, int ngw, int lane, int wave) {
;     ...
;     cvt8(a.in[2], (bf16*)(cb + C_KDC), (size_t)CACHE_ROWS * 128, gt, ngt);
;     cvt8(a.in[3], (bf16*)(cb + C_VDC), (size_t)CACHE_ROWS * 128, gt, ngt);
.Lcvk_tail_a:
	s_waitcnt vmcnt(6)
	v_cvt_pk_bf16_f32 v100, v100, v101
	v_cvt_pk_bf16_f32 v101, v102, v103
	v_cvt_pk_bf16_f32 v102, v104, v105
	v_cvt_pk_bf16_f32 v103, v106, v107
	global_store_dwordx4 v[12:13], v[100:103], off
	v_lshl_add_u64 v[12:13], v[12:13], 0, s[18:19]
	s_waitcnt vmcnt(5)
	v_cvt_pk_bf16_f32 v108, v108, v109
	v_cvt_pk_bf16_f32 v109, v110, v111
	v_cvt_pk_bf16_f32 v110, v112, v113
	v_cvt_pk_bf16_f32 v111, v114, v115
	global_store_dwordx4 v[12:13], v[108:111], off
	v_lshl_add_u64 v[12:13], v[12:13], 0, s[18:19]
	s_waitcnt vmcnt(4)
	v_cvt_pk_bf16_f32 v116, v116, v117
	v_cvt_pk_bf16_f32 v117, v118, v119
	v_cvt_pk_bf16_f32 v118, v120, v121
	v_cvt_pk_bf16_f32 v119, v122, v123
	global_store_dwordx4 v[12:13], v[116:119], off
	v_lshl_add_u64 v[12:13], v[12:13], 0, s[18:19]
	s_waitcnt vmcnt(3)
	v_cvt_pk_bf16_f32 v124, v124, v125
	v_cvt_pk_bf16_f32 v125, v126, v127
	v_cvt_pk_bf16_f32 v126, v128, v129
	v_cvt_pk_bf16_f32 v127, v130, v131
	global_store_dwordx4 v[12:13], v[124:127], off
	v_lshl_add_u64 v[12:13], v[12:13], 0, s[18:19]
	s_branch .Lcvk_rem
.Lcvk_tail_b:
	s_waitcnt vmcnt(6)
	v_cvt_pk_bf16_f32 v132, v132, v133
	v_cvt_pk_bf16_f32 v133, v134, v135
	v_cvt_pk_bf16_f32 v134, v136, v137
	v_cvt_pk_bf16_f32 v135, v138, v139
	global_store_dwordx4 v[12:13], v[132:135], off
	v_lshl_add_u64 v[12:13], v[12:13], 0, s[18:19]
	s_waitcnt vmcnt(5)
	v_cvt_pk_bf16_f32 v140, v140, v141
	v_cvt_pk_bf16_f32 v141, v142, v143
	v_cvt_pk_bf16_f32 v142, v144, v145
	v_cvt_pk_bf16_f32 v143, v146, v147
	global_store_dwordx4 v[12:13], v[140:143], off
	v_lshl_add_u64 v[12:13], v[12:13], 0, s[18:19]
	s_waitcnt vmcnt(4)
	v_cvt_pk_bf16_f32 v148, v148, v149
	v_cvt_pk_bf16_f32 v149, v150, v151
	v_cvt_pk_bf16_f32 v150, v152, v153
	v_cvt_pk_bf16_f32 v151, v154, v155
	global_store_dwordx4 v[12:13], v[148:151], off
	v_lshl_add_u64 v[12:13], v[12:13], 0, s[18:19]
	s_waitcnt vmcnt(3)
	v_cvt_pk_bf16_f32 v156, v156, v157
	v_cvt_pk_bf16_f32 v157, v158, v159
	v_cvt_pk_bf16_f32 v158, v160, v161
	v_cvt_pk_bf16_f32 v159, v162, v163
	global_store_dwordx4 v[12:13], v[156:159], off
	v_lshl_add_u64 v[12:13], v[12:13], 0, s[18:19]
.Lcvk_rem:
	s_cmp_lt_u32 s14, 0x400000
	s_cbranch_scc0 .Lcvk_done
.Lcvk_rem_loop:
	global_load_dwordx4 v[100:103], v[10:11], off nt
	global_load_dwordx4 v[104:107], v[10:11], off offset:16 nt
	v_lshl_add_u64 v[10:11], v[10:11], 0, s[16:17]
	s_add_u32 s14, s14, s90
	s_waitcnt vmcnt(0)
	v_cvt_pk_bf16_f32 v100, v100, v101
	v_cvt_pk_bf16_f32 v101, v102, v103
	v_cvt_pk_bf16_f32 v102, v104, v105
	v_cvt_pk_bf16_f32 v103, v106, v107
	global_store_dwordx4 v[12:13], v[100:103], off
	v_lshl_add_u64 v[12:13], v[12:13], 0, s[18:19]
	s_cmp_lt_u32 s14, 0x400000
	s_cbranch_scc1 .Lcvk_rem_loop
.Lcvk_done:
	v_mov_b64_e32 v[10:11], v[14:15]
	s_lshl_b64 s[12:13], s[6:7], 10
	s_add_u32 s12, s4, s12
	s_addc_u32 s13, s5, s13
	s_add_u32 s12, s12, 0x31e00000
	s_addc_u32 s13, s13, 0
	v_lshl_add_u64 v[12:13], s[12:13], 0, v[4:5]
	s_mov_b32 s14, s2
	s_sub_i32 s15, 0x400000, s11
	s_cmp_lt_i32 s14, s15
	s_cbranch_scc0 .Lcvv_rem
	global_load_dwordx4 v[100:103], v[10:11], off nt
	global_load_dwordx4 v[104:107], v[10:11], off offset:16 nt
	v_lshl_add_u64 v[10:11], v[10:11], 0, s[16:17]
	global_load_dwordx4 v[108:111], v[10:11], off nt
	global_load_dwordx4 v[112:115], v[10:11], off offset:16 nt
	v_lshl_add_u64 v[10:11], v[10:11], 0, s[16:17]
	global_load_dwordx4 v[116:119], v[10:11], off nt
	global_load_dwordx4 v[120:123], v[10:11], off offset:16 nt
	v_lshl_add_u64 v[10:11], v[10:11], 0, s[16:17]
	global_load_dwordx4 v[124:127], v[10:11], off nt
	global_load_dwordx4 v[128:131], v[10:11], off offset:16 nt
	v_lshl_add_u64 v[10:11], v[10:11], 0, s[16:17]
	s_add_u32 s14, s14, s10

; __device__ __forceinline__ unsigned pk2(float lo, float hi) { f32x2 v = {lo, hi}; bf16x2_hw b = __builtin_convertvector(v, bf16x2_hw); return __builtin_bit_cast(unsigned, b); }
; __device__ __forceinline__ void cvt8(const float* src, bf16* dst, size_t n8, size_t gt, size_t ngt) {
;     for (size_t i = gt; i < n8; i += ngt) { const f32x4 a = __builtin_nontemporal_load((const f32x4*)src + 2 * i), b = __builtin_nontemporal_load((const f32x4*)src + 2 * i + 1);
;         ((u32x4*)dst)[i] = (u32x4){pk2(a[0], a[1]), pk2(a[2], a[3]), pk2(b[0], b[1]), pk2(b[2], b[3])}; }
; }
; __device__ __forceinline__ void phase_prologue(const Args& a, LAS unsigned char* lds, int gw, int ngw, int lane, int wave) {
;     ...
;     cvt8(a.in[4], (bf16*)(cb + C_CKVC), (size_t)CACHE_ROWS * 32, gt, ngt);
.Lcvv_done:
	v_mov_b64_e32 v[10:11], v[16:17]
	s_lshl_b64 s[12:13], s[6:7], 10
	s_add_u32 s12, s4, s12
	s_addc_u32 s13, s5, s13
	s_add_u32 s12, s12, 0x3de00000
	s_addc_u32 s13, s13, 0
	v_lshl_add_u64 v[12:13], s[12:13], 0, v[4:5]
	s_mov_b32 s14, s2
	s_sub_i32 s15, 0x100000, s11
	s_cmp_lt_i32 s14, s15
	s_cbranch_scc0 .Lcvc_rem
	global_load_dwordx4 v[100:103], v[10:11], off nt
	global_load_dwordx4 v[104:107], v[10:11], off offset:16 nt
	v_lshl_add_u64 v[10:11], v[10:11], 0, s[16:17]
	global_load_dwordx4 v[108:111], v[10:11], off nt
	global_load_dwordx4 v[112:115], v[10:11], off offset:16 nt
	v_lshl_add_u64 v[10:11], v[10:11], 0, s[16:17]
	global_load_dwordx4 v[116:119], v[10:11], off nt
	global_load_dwordx4 v[120:123], v[10:11], off offset:16 nt
	v_lshl_add_u64 v[10:11], v[10:11], 0, s[16:17]
	global_load_dwordx4 v[124:127], v[10:11], off nt
	global_load_dwordx4 v[128:131], v[10:11], off offset:16 nt
	v_lshl_add_u64 v[10:11], v[10:11], 0, s[16:17]
	s_add_u32 s14, s14, s10

; __device__ __forceinline__ unsigned pk2(float lo, float hi) { f32x2 v = {lo, hi}; bf16x2_hw b = __builtin_convertvector(v, bf16x2_hw); return __builtin_bit_cast(unsigned, b); }
; __device__ __forceinline__ void cvt8(const float* src, bf16* dst, size_t n8, size_t gt, size_t ngt) {
;     for (size_t i = gt; i < n8; i += ngt) { const f32x4 a = __builtin_nontemporal_load((const f32x4*)src + 2 * i), b = __builtin_nontemporal_load((const f32x4*)src + 2 * i + 1);
;         ((u32x4*)dst)[i] = (u32x4){pk2(a[0], a[1]), pk2(a[2], a[3]), pk2(b[0], b[1]), pk2(b[2], b[3])}; }
; }
; __device__ __forceinline__ void phase_prologue(const Args& a, LAS unsigned char* lds, int gw, int ngw, int lane, int wave) {
;     ...
;     cvt8(a.in[4], (bf16*)(cb + C_CKVC), (size_t)CACHE_ROWS * 32, gt, ngt);
;     cvt8(a.in[5], (bf16*)(cb + C_KRC), (size_t)CACHE_ROWS * 4, gt, ngt);
.Lcvc_rem:
	s_cmp_lt_u32 s14, 0x100000
	s_cbranch_scc0 .Lcvc_done
.Lcvc_rem_loop:
	global_load_dwordx4 v[100:103], v[10:11], off nt
	global_load_dwordx4 v[104:107], v[10:11], off offset:16 nt
	v_lshl_add_u64 v[10:11], v[10:11], 0, s[16:17]
	s_add_u32 s14, s14, s90
	s_waitcnt vmcnt(0)
	v_cvt_pk_bf16_f32 v100, v100, v101
	v_cvt_pk_bf16_f32 v101, v102, v103
	v_cvt_pk_bf16_f32 v102, v104, v105
	v_cvt_pk_bf16_f32 v103, v106, v107
	global_store_dwordx4 v[12:13], v[100:103], off
	v_lshl_add_u64 v[12:13], v[12:13], 0, s[18:19]
	s_cmp_lt_u32 s14, 0x100000
	s_cbranch_scc1 .Lcvc_rem_loop
.Lcvc_done:
	v_mov_b64_e32 v[10:11], v[18:19]
	s_lshl_b64 s[12:13], s[6:7], 10
	s_add_u32 s12, s4, s12
	s_addc_u32 s13, s5, s13
	s_add_u32 s12, s12, 0x3ee00000
	s_addc_u32 s13, s13, 0
	v_lshl_add_u64 v[12:13], s[12:13], 0, v[4:5]
	s_mov_b32 s14, s2
	s_sub_i32 s15, 0x20000, s11
	s_cmp_lt_i32 s14, s15
	s_cbranch_scc0 .Lcvr_rem
	global_load_dwordx4 v[100:103], v[10:11], off nt
	global_load_dwordx4 v[104:107], v[10:11], off offset:16 nt
	v_lshl_add_u64 v[10:11], v[10:11], 0, s[16:17]
	global_load_dwordx4 v[108:111], v[10:11], off nt
	global_load_dwordx4 v[112:115], v[10:11], off offset:16 nt
	v_lshl_add_u64 v[10:11], v[10:11], 0, s[16:17]
	global_load_dwordx4 v[116:119], v[10:11], off nt
	global_load_dwordx4 v[120:123], v[10:11], off offset:16 nt
	v_lshl_add_u64 v[10:11], v[10:11], 0, s[16:17]
	global_load_dwordx4 v[124:127], v[10:11], off nt
	global_load_dwordx4 v[128:131], v[10:11], off offset:16 nt
	v_lshl_add_u64 v[10:11], v[10:11], 0, s[16:17]
	s_add_u32 s14, s14, s10

; __device__ __forceinline__ unsigned pk2(float lo, float hi) { f32x2 v = {lo, hi}; bf16x2_hw b = __builtin_convertvector(v, bf16x2_hw); return __builtin_bit_cast(unsigned, b); }
; __device__ __forceinline__ void cvt8(const float* src, bf16* dst, size_t n8, size_t gt, size_t ngt) {
;     for (size_t i = gt; i < n8; i += ngt) { const f32x4 a = __builtin_nontemporal_load((const f32x4*)src + 2 * i), b = __builtin_nontemporal_load((const f32x4*)src + 2 * i + 1);
;         ((u32x4*)dst)[i] = (u32x4){pk2(a[0], a[1]), pk2(a[2], a[3]), pk2(b[0], b[1]), pk2(b[2], b[3])}; }
; }
; __device__ __forceinline__ void phase_prologue(const Args& a, LAS unsigned char* lds, int gw, int ngw, int lane, int wave) {
;     ...
;     cvt8(a.in[5], (bf16*)(cb + C_KRC), (size_t)CACHE_ROWS * 4, gt, ngt);
;     float* tab = (float*)(ws + WS_TAB);
;     for (size_t i = gt; i < 8 * 192; i += ngt) {
;         const int h = (int)i / 192, idx = (int)i % 192, rel = idx - 128, n = rel < 0 ? -rel : rel;
;         int bucket = n;
;         if (n >= 8) { int j = (31 - __clz(n * n)) - 6; bucket = 8 + j; if (bucket > 15) bucket = 15; }
;         if (rel > 0) bucket += 16;
;         tab[i] = (a.in[6][bucket * 8 + h] - a.in[6][15 * 8 + h]) * LOG2E;
.Lcvr_rem:
	s_cmp_lt_u32 s14, 0x20000
	s_cbranch_scc0 .Lcvr_done
.Lcvr_rem_loop:
	global_load_dwordx4 v[100:103], v[10:11], off nt
	global_load_dwordx4 v[104:107], v[10:11], off offset:16 nt
	v_lshl_add_u64 v[10:11], v[10:11], 0, s[16:17]
	s_add_u32 s14, s14, s90
	s_waitcnt vmcnt(0)
	v_cvt_pk_bf16_f32 v100, v100, v101
	v_cvt_pk_bf16_f32 v101, v102, v103
	v_cvt_pk_bf16_f32 v102, v104, v105
	v_cvt_pk_bf16_f32 v103, v106, v107
	global_store_dwordx4 v[12:13], v[100:103], off
	v_lshl_add_u64 v[12:13], v[12:13], 0, s[18:19]
	s_cmp_lt_u32 s14, 0x20000
	s_cbranch_scc1 .Lcvr_rem_loop
.Lcvr_done:
.LBB0_97:
	v_mov_b64_e32 v[2:3], 0x5ff
	v_cmp_gt_u64_e32 vcc, s[2:3], v[2:3]
	s_mov_b64 s[10:11], 0x5ff
	s_cbranch_vccnz .LBB0_101
	s_lshl_b64 s[12:13], s[6:7], 8
	s_add_u32 s12, s4, s12
	v_lshlrev_b32_e32 v2, 2, v66
	v_mov_b32_e32 v3, 0
	s_addc_u32 s13, s5, s13
	v_lshl_add_u64 v[2:3], s[12:13], 0, v[2:3]
	s_lshl_b64 s[14:15], s[82:83], 8
	s_mov_b64 s[12:13], 0
	s_mov_b32 s16, 0xaaab
	s_movk_i32 s17, 0x80
	v_mov_b64_e32 v[4:5], v[6:7]
